# indexer pass header: each wave loads 1/8 of the shared query fragments and weights, exchanged through LDS (two extra workgroup barriers), dead address math removed
# speedup vs baseline: 1.0179x; 1.0179x over previous
; #define GAS __attribute__((address_space(1)))
; __device__ __forceinline__ void indexer_unit(const Args& a, LAS unsigned char* lds, LAS unsigned long long* maskl, int b, int qblk, int wave, int lane) {
;     ...
;     bf16x8 af[8][2]; float wv[8][4];
; #pragma unroll
;     for (int rt = 0; rt < 8; ++rt) {
;         const GAS bf16* p = z + (rowb + t0 + 2 * rt + (fr >> 3)) * ZW + ZIQ + (fr & 7) * 64 + 8 * fq;
;         af[rt][0] = __builtin_nontemporal_load((const GAS bf16x8*)p); af[rt][1] = __builtin_nontemporal_load((const GAS bf16x8*)(p + 32));
;         const u32x2 w = *(const GAS u32x2*)(z + (rowb + t0 + 2 * rt + (fq >> 1)) * ZW + ZIW + 4 * (fq & 1));
;         wv[rt][0] = bflo(w.x); wv[rt][1] = bfhi(w.x); wv[rt][2] = bflo(w.y); wv[rt][3] = bfhi(w.y);
;     }
;     const int nkt = qblk + 1;
;     bf16x8 nb0, nb1;
;     { const int k0 = wave < nkt ? wave : 0; const GAS bf16* p = ikn + (rowb + 16 * k0 + fr) * 64 + 8 * fq; nb0 = *(const GAS bf16x8*)p; nb1 = *(const GAS bf16x8*)(p + 32); }
.LBB0_1082:
	v_readlane_b32 s2, v254, 44
	v_mov_b32_e32 v76, v252
	s_or_b32 s9, s8, s2
	s_lshl_b32 s76, s9, 4
	v_and_b32_e32 v5, 63, v76
	v_readlane_b32 s2, v254, 4
	s_cmp_gt_u32 s2, s9
	v_lshlrev_b32_e32 v84, 6, v5
	s_cbranch_scc1 .Lhs_skip
	v_readlane_b32 s14, v254, 46
	v_readlane_b32 s4, v254, 24
	s_add_i32 s2, s76, s14
	v_bfe_u32 v57, v76, 3, 1
	v_readlane_b32 s5, v254, 25
	v_and_b32_e32 v2, 0x1c0, v84
	s_nop 0
	v_mov_b64_e32 v[46:47], s[4:5]
	s_movk_i32 s10, 0x1e00
	v_lshlrev_b32_e32 v48, 1, v2
	v_mov_b32_e32 v49, v4
	v_lshrrev_b32_e32 v119, 5, v5
	v_and_b32_e32 v74, 48, v5
	v_mov_b32_e32 v75, v4
	s_mov_b64 s[12:13], 0x1900
	s_or_b32 s3, s2, 2
	s_movk_i32 s11, 0x1000
	s_or_b32 s3, s2, 4
	s_or_b32 s3, s2, 6
	s_or_b32 s3, s2, 8
	s_or_b32 s3, s2, 10
	s_or_b32 s3, s2, 12
	v_or_b32_e32 v54, s3, v57
	v_mad_u64_u32 v[54:55], s[4:5], v54, s10, v[46:47]
	v_lshl_add_u64 v[54:55], v[54:55], 0, v[48:49]
	v_lshl_add_u64 v[54:55], v[54:55], 0, v[74:75]
	v_add_co_u32_e32 v56, vcc, s11, v54
	s_mov_b64 s[6:7], vcc
	s_or_b32 s4, s2, 14
	v_and_b32_e32 v77, 15, v76
	v_readlane_b32 s2, v254, 47
	s_nop 1
	v_or_b32_e32 v66, s2, v77
	v_mov_b32_e32 v67, v4
	v_readlane_b32 s2, v254, 26
	v_lshlrev_b64 v[66:67], 7, v[66:67]
	v_readlane_b32 s3, v254, 27
	s_nop 1
	v_lshl_add_u64 v[66:67], s[2:3], 0, v[66:67]
	v_lshl_add_u64 v[70:71], v[66:67], 0, v[74:75]
	v_cmp_lt_i32_e32 vcc, v227, v226
	global_load_dwordx4 v[66:69], v[70:71], off offset:64
	global_load_dwordx4 v[70:73], v[70:71], off
	v_readlane_b32 s98, v254, 24
	v_readlane_b32 s99, v254, 25
	v_readlane_b32 s100, v254, 46
	v_bfe_u32 v86, v252, 3, 1
	v_lshrrev_b32_e32 v87, 5, v5
	v_and_b32_e32 v88, 7, v5
	s_add_i32 s100, s100, s76
	s_add_i32 s100, s100, s85
	v_and_b32_e32 v89, 48, v5
	v_lshl_or_b32 v88, v88, 7, v89
	v_or_b32_e32 v86, s100, v86
	v_or_b32_e32 v87, s100, v87
	s_movk_i32 s101, 0x1900
	s_movk_i32 s100, 0x1d90
	v_mul_u32_u24_e32 v86, 0x1e00, v86
	v_mul_u32_u24_e32 v87, 0x1e00, v87
	v_lshrrev_b32_e32 v89, 1, v5
	v_and_b32_e32 v89, 8, v89
	v_add3_u32 v86, v86, v88, s101
	v_add3_u32 v87, v87, v89, s100
	global_load_dwordx4 v[90:93], v86, s[98:99] nt
	global_load_dwordx4 v[94:97], v86, s[98:99] offset:64 nt
	global_load_dwordx2 v[98:99], v87, s[98:99]
	s_lshl_b32 s100, s85, 10
	s_lshl_b32 s101, s85, 8
	v_lshl_add_u32 v88, v5, 4, s100
	v_lshl_add_u32 v89, v5, 3, s101
	s_waitcnt vmcnt(0)
	ds_write_b128 v88, v[90:93]
	ds_write_b128 v88, v[94:97] offset:1024
	ds_write_b64 v89, v[98:99] offset:16384
	s_waitcnt lgkmcnt(0)
	s_barrier
	v_lshlrev_b32_e32 v88, 4, v5
	v_lshlrev_b32_e32 v89, 3, v5
	ds_read_b128 v[0:3], v88 offset:0
	ds_read_b128 v[6:9], v88 offset:1024
	ds_read_b128 v[14:17], v88 offset:2048
	ds_read_b128 v[10:13], v88 offset:3072
	ds_read_b128 v[18:21], v88 offset:4096
	ds_read_b128 v[22:25], v88 offset:5120
	ds_read_b128 v[30:33], v88 offset:6144
	ds_read_b128 v[26:29], v88 offset:7168
	ds_read_b128 v[34:37], v88 offset:8192
	ds_read_b128 v[38:41], v88 offset:9216
	ds_read_b128 v[42:45], v88 offset:10240
	ds_read_b128 v[50:53], v88 offset:11264
	ds_read_b128 v[54:57], v88 offset:12288
	ds_read_b128 v[58:61], v88 offset:13312
	ds_read_b128 v[46:49], v88 offset:14336
	ds_read_b128 v[62:65], v88 offset:15360
	ds_read_b64 v[78:79], v89 offset:16384
	ds_read_b64 v[80:81], v89 offset:16896
	ds_read_b64 v[82:83], v89 offset:17408
	ds_read_b64 v[100:101], v89 offset:17920
	ds_read_b64 v[104:105], v89 offset:18432
	ds_read_b64 v[108:109], v89 offset:18944
	ds_read_b64 v[112:113], v89 offset:19456
	ds_read_b64 v[116:117], v89 offset:19968
	s_waitcnt lgkmcnt(0)
	s_barrier
	s_waitcnt vmcnt(0)
	v_lshlrev_b32_e32 v93, 16, v82
	v_and_b32_e32 v94, 0xffff0000, v82
	v_lshlrev_b32_e32 v95, 16, v83
	v_and_b32_e32 v96, 0xffff0000, v83
	v_lshl_add_u64 v[82:83], s[2:3], 0, v[74:75]
	v_cndmask_b32_e32 v74, v253, v227, vcc
	v_lshlrev_b32_e32 v118, 2, v74
	v_and_b32_e32 v74, 16, v76
	v_cmp_eq_u32_e64 s[6:7], 0, v74
	v_lshlrev_b32_e32 v74, 2, v77
	v_lshl_or_b32 v74, v119, 13, v74
	v_readlane_b32 s2, v254, 36
	v_lshlrev_b32_e32 v85, 16, v78
	v_and_b32_e32 v86, 0xffff0000, v78
	v_lshlrev_b32_e32 v87, 16, v79
	v_and_b32_e32 v88, 0xffff0000, v79
	v_lshlrev_b32_e32 v89, 16, v80
	v_and_b32_e32 v90, 0xffff0000, v80
	v_lshlrev_b32_e32 v91, 16, v81
	v_and_b32_e32 v92, 0xffff0000, v81
	v_lshlrev_b32_e32 v97, 16, v100
	v_and_b32_e32 v98, 0xffff0000, v100
	v_lshlrev_b32_e32 v99, 16, v101
	v_and_b32_e32 v100, 0xffff0000, v101
	v_lshlrev_b32_e32 v101, 16, v104
	v_and_b32_e32 v102, 0xffff0000, v104
	v_lshlrev_b32_e32 v103, 16, v105
	v_and_b32_e32 v104, 0xffff0000, v105
	v_lshlrev_b32_e32 v105, 16, v108
	v_and_b32_e32 v106, 0xffff0000, v108
	v_lshlrev_b32_e32 v107, 16, v109
	v_and_b32_e32 v108, 0xffff0000, v109
	v_add_u32_e32 v119, s2, v74
	v_readlane_b32 s10, v254, 4
	v_lshlrev_b32_e32 v109, 16, v112
	v_and_b32_e32 v110, 0xffff0000, v112
	v_lshlrev_b32_e32 v111, 16, v113
	v_and_b32_e32 v112, 0xffff0000, v113
	v_lshlrev_b32_e32 v113, 16, v116
	v_and_b32_e32 v114, 0xffff0000, v116
	v_lshlrev_b32_e32 v115, 16, v117
	v_and_b32_e32 v116, 0xffff0000, v117
	v_or_b32_e32 v117, s14, v77
	s_branch .LBB0_1085

; #define GAS __attribute__((address_space(1)))
; __device__ __forceinline__ void indexer_unit(const Args& a, LAS unsigned char* lds, LAS unsigned long long* maskl, int b, int qblk, int wave, int lane) {
;     ...
;     bf16x8 af[8][2]; float wv[8][4];
; #pragma unroll
;     for (int rt = 0; rt < 8; ++rt) {
;         const GAS bf16* p = z + (rowb + t0 + 2 * rt + (fr >> 3)) * ZW + ZIQ + (fr & 7) * 64 + 8 * fq;
;         af[rt][0] = __builtin_nontemporal_load((const GAS bf16x8*)p); af[rt][1] = __builtin_nontemporal_load((const GAS bf16x8*)(p + 32));
;         const u32x2 w = *(const GAS u32x2*)(z + (rowb + t0 + 2 * rt + (fq >> 1)) * ZW + ZIW + 4 * (fq & 1));
;         wv[rt][0] = bflo(w.x); wv[rt][1] = bfhi(w.x); wv[rt][2] = bflo(w.y); wv[rt][3] = bfhi(w.y);
;     }
.Lhs_skip:
	v_readlane_b32 s98, v254, 24
	v_readlane_b32 s99, v254, 25
	v_readlane_b32 s100, v254, 46
	v_bfe_u32 v86, v252, 3, 1
	v_lshrrev_b32_e32 v87, 5, v5
	v_and_b32_e32 v88, 7, v5
	s_add_i32 s100, s100, s76
	s_add_i32 s100, s100, s85
	v_and_b32_e32 v89, 48, v5
	v_lshl_or_b32 v88, v88, 7, v89
	v_or_b32_e32 v86, s100, v86
	v_or_b32_e32 v87, s100, v87
	s_movk_i32 s101, 0x1900
	s_movk_i32 s100, 0x1d90
	v_mul_u32_u24_e32 v86, 0x1e00, v86
	v_mul_u32_u24_e32 v87, 0x1e00, v87
	v_lshrrev_b32_e32 v89, 1, v5
	v_and_b32_e32 v89, 8, v89
	v_add3_u32 v86, v86, v88, s101
	v_add3_u32 v87, v87, v89, s100
	global_load_dwordx4 v[90:93], v86, s[98:99] nt
	global_load_dwordx4 v[94:97], v86, s[98:99] offset:64 nt
	global_load_dwordx2 v[98:99], v87, s[98:99]
	s_lshl_b32 s100, s85, 10
	s_lshl_b32 s101, s85, 8
	v_lshl_add_u32 v88, v5, 4, s100
	v_lshl_add_u32 v89, v5, 3, s101
	s_waitcnt vmcnt(0)
	ds_write_b128 v88, v[90:93]
	ds_write_b128 v88, v[94:97] offset:1024
	ds_write_b64 v89, v[98:99] offset:16384
	s_waitcnt lgkmcnt(0)
	s_barrier
	s_barrier

; __global__ void __launch_bounds__(512, 2) mk_fwd(Args a) {
	.amdhsa_kernel _Z6mk_fwd4Args
		.amdhsa_group_segment_fixed_size 0
		.amdhsa_private_segment_fixed_size 0
		.amdhsa_kernarg_size 488
		.amdhsa_user_sgpr_count 2
		.amdhsa_user_sgpr_dispatch_ptr 0
		.amdhsa_user_sgpr_queue_ptr 0
		.amdhsa_user_sgpr_kernarg_segment_ptr 1
		.amdhsa_user_sgpr_dispatch_id 0
		.amdhsa_user_sgpr_kernarg_preload_length 0
		.amdhsa_user_sgpr_kernarg_preload_offset 0
		.amdhsa_user_sgpr_private_segment_size 0
		.amdhsa_uses_dynamic_stack 0
		.amdhsa_enable_private_segment 0
		.amdhsa_system_sgpr_workgroup_id_x 1
		.amdhsa_system_sgpr_workgroup_id_y 0
		.amdhsa_system_sgpr_workgroup_id_z 0
		.amdhsa_system_sgpr_workgroup_info 0
		.amdhsa_system_vgpr_workitem_id 2
		.amdhsa_next_free_vgpr 255
		.amdhsa_next_free_sgpr 102
		.amdhsa_accum_offset 256
		.amdhsa_reserve_vcc 1
		.amdhsa_float_round_mode_32 0
		.amdhsa_float_round_mode_16_64 0
		.amdhsa_float_denorm_mode_32 3
		.amdhsa_float_denorm_mode_16_64 3
		.amdhsa_dx10_clamp 1
		.amdhsa_ieee_mode 1
		.amdhsa_fp16_overflow 0
		.amdhsa_tg_split 0
		.amdhsa_exception_fp_ieee_invalid_op 0
		.amdhsa_exception_fp_denorm_src 0
		.amdhsa_exception_fp_ieee_div_zero 0
		.amdhsa_exception_fp_ieee_overflow 0
		.amdhsa_exception_fp_ieee_underflow 0
		.amdhsa_exception_fp_ieee_inexact 0
		.amdhsa_exception_int_div_zero 0
	.end_amdhsa_kernel

amdhsa.kernels:
  - .agpr_count:     0
    .args:
      - .offset:         0
        .size:           232
        .value_kind:     by_value
      - .offset:         232
        .size:           4
        .value_kind:     hidden_block_count_x
      - .offset:         236
        .size:           4
        .value_kind:     hidden_block_count_y
      - .offset:         240
        .size:           4
        .value_kind:     hidden_block_count_z
      - .offset:         244
        .size:           2
        .value_kind:     hidden_group_size_x
      - .offset:         246
        .size:           2
        .value_kind:     hidden_group_size_y
      - .offset:         248
        .size:           2
        .value_kind:     hidden_group_size_z
      - .offset:         250
        .size:           2
        .value_kind:     hidden_remainder_x
      - .offset:         252
        .size:           2
        .value_kind:     hidden_remainder_y
      - .offset:         254
        .size:           2
        .value_kind:     hidden_remainder_z
      - .offset:         272
        .size:           8
        .value_kind:     hidden_global_offset_x
      - .offset:         280
        .size:           8
        .value_kind:     hidden_global_offset_y
      - .offset:         288
        .size:           8
        .value_kind:     hidden_global_offset_z
      - .offset:         296
        .size:           2
        .value_kind:     hidden_grid_dims
      - .offset:         320
        .size:           8
        .value_kind:     hidden_multigrid_sync_arg
      - .offset:         352
        .size:           4
        .value_kind:     hidden_dynamic_lds_size
    .group_segment_fixed_size: 0
    .kernarg_segment_align: 8
    .kernarg_segment_size: 488
    .language:       OpenCL C
    .language_version:
      - 2
      - 0
    .max_flat_workgroup_size: 512
    .name:           _Z6mk_fwd4Args
    .private_segment_fixed_size: 0
    .sgpr_count:     108
    .sgpr_spill_count: 55
    .symbol:         _Z6mk_fwd4Args.kd
    .uniform_work_group_size: 1
    .uses_dynamic_stack: false
    .vgpr_count:     255
    .vgpr_spill_count: 0
    .wavefront_size: 64
